# v80 + unreachable s_nop padding after five s_branch instructions so the GEMM K-loop heads sit at their baseline byte phase (mod 64)
# speedup vs baseline: 1.0010x; 1.0010x over previous
.LBB0_79:
	s_mov_b32 s0, s12
	v_writelane_b32 v255, s0, 22
	s_ashr_i32 s13, s12, 31
	s_mov_b32 s97, s21
	v_writelane_b32 v255, s1, 23
	s_lshl_b64 s[0:1], s[12:13], 18
	v_readlane_b32 s6, v255, 24
	s_add_u32 s16, s6, s0
	v_readlane_b32 s0, v255, 40
	s_addc_u32 s17, s0, s1
	s_and_b64 s[0:1], s[46:47], exec
	s_cselect_b32 s14, s17, s3
	s_cselect_b32 s15, s16, s2
	s_cmp_eq_u32 s8, 0
	s_cselect_b64 s[0:1], -1, 0
	s_and_b64 s[6:7], s[0:1], exec
	s_cselect_b32 s64, 0x40000, 0
	s_cmp_eq_u32 s21, 0
	s_cselect_b32 s20, 0x40000, 0
	s_ashr_i32 s43, s42, 31
	s_lshl_b64 s[6:7], s[42:43], 19
	v_readlane_b32 s8, v255, 13
	s_add_u32 s34, s8, s6
	v_readlane_b32 s6, v255, 26
	s_addc_u32 s35, s6, s7
	s_and_b64 s[6:7], s[46:47], exec
	s_cselect_b32 s12, s35, s5
	s_cselect_b32 s13, s34, s4
	s_add_u32 s21, s4, 0x100
	s_addc_u32 s29, s5, 0
	s_add_u32 s4, s2, 0x80
	s_addc_u32 s5, s3, 0
	v_lshl_add_u64 v[0:1], s[4:5], 0, v[220:221]
	v_lshl_add_u64 v[224:225], v[0:1], 0, s[64:65]
	v_lshl_add_u64 v[0:1], s[4:5], 0, v[222:223]
	v_mov_b32_e32 v160, v161
	v_lshl_add_u64 v[226:227], v[0:1], 0, s[64:65]
	s_waitcnt lgkmcnt(0)
	v_mov_b32_e32 v162, v161
	v_mov_b32_e32 v163, v161
	v_mov_b32_e32 v64, 0
	v_mov_b64_e32 v[0:1], v[160:161]
	v_mov_b64_e32 v[4:5], v[160:161]
	v_mov_b64_e32 v[16:17], v[160:161]
	v_mov_b64_e32 v[20:21], v[160:161]
	v_mov_b64_e32 v[32:33], v[160:161]
	v_mov_b64_e32 v[36:37], v[160:161]
	v_mov_b64_e32 v[48:49], v[160:161]
	v_mov_b64_e32 v[52:53], v[160:161]
	v_mov_b64_e32 v[8:9], v[160:161]
	v_mov_b64_e32 v[12:13], v[160:161]
	v_mov_b64_e32 v[24:25], v[160:161]
	v_mov_b64_e32 v[28:29], v[160:161]
	v_mov_b64_e32 v[40:41], v[160:161]
	v_mov_b64_e32 v[44:45], v[160:161]
	v_mov_b64_e32 v[56:57], v[160:161]
	v_mov_b64_e32 v[60:61], v[160:161]
	s_mov_b32 s39, -2
	s_mov_b64 s[4:5], 0
	v_mov_b64_e32 v[2:3], v[162:163]
	v_mov_b64_e32 v[6:7], v[162:163]
	v_mov_b64_e32 v[18:19], v[162:163]
	v_mov_b64_e32 v[22:23], v[162:163]
	v_mov_b64_e32 v[34:35], v[162:163]
	v_mov_b64_e32 v[38:39], v[162:163]
	v_mov_b64_e32 v[50:51], v[162:163]
	v_mov_b64_e32 v[54:55], v[162:163]
	v_mov_b64_e32 v[10:11], v[162:163]
	v_mov_b64_e32 v[14:15], v[162:163]
	v_mov_b64_e32 v[26:27], v[162:163]
	v_mov_b64_e32 v[30:31], v[162:163]
	v_mov_b64_e32 v[42:43], v[162:163]
	v_mov_b64_e32 v[46:47], v[162:163]
	v_mov_b64_e32 v[58:59], v[162:163]
	v_mov_b64_e32 v[62:63], v[162:163]
	v_mov_b32_e32 v65, v64
	v_mov_b32_e32 v66, v64
	v_mov_b32_e32 v67, v64
	v_mov_b32_e32 v68, v64
	v_mov_b32_e32 v69, v64
	v_mov_b32_e32 v70, v64
	v_mov_b32_e32 v71, v64
	v_mov_b32_e32 v80, v64
	v_mov_b32_e32 v81, v64
	v_mov_b32_e32 v82, v64
	v_mov_b32_e32 v83, v64
	v_mov_b32_e32 v84, v64
	v_mov_b32_e32 v85, v64
	v_mov_b32_e32 v86, v64
	v_mov_b32_e32 v87, v64
	v_mov_b32_e32 v96, v64
	v_mov_b32_e32 v97, v64
	v_mov_b32_e32 v98, v64
	v_mov_b32_e32 v99, v64
	v_mov_b32_e32 v100, v64
	v_mov_b32_e32 v101, v64
	v_mov_b32_e32 v102, v64
	v_mov_b32_e32 v103, v64
	v_mov_b32_e32 v112, v64
	v_mov_b32_e32 v113, v64
	v_mov_b32_e32 v114, v64
	v_mov_b32_e32 v115, v64
	v_mov_b32_e32 v116, v64
	v_mov_b32_e32 v117, v64
	v_mov_b32_e32 v118, v64
	v_mov_b32_e32 v119, v64
	v_mov_b32_e32 v72, v64
	v_mov_b32_e32 v73, v64
	v_mov_b32_e32 v74, v64
	v_mov_b32_e32 v75, v64
	v_mov_b32_e32 v76, v64
	v_mov_b32_e32 v77, v64
	v_mov_b32_e32 v78, v64
	v_mov_b32_e32 v79, v64
	v_mov_b32_e32 v88, v64
	v_mov_b32_e32 v89, v64
	v_mov_b32_e32 v90, v64
	v_mov_b32_e32 v91, v64
	v_mov_b32_e32 v92, v64
	v_mov_b32_e32 v93, v64
	v_mov_b32_e32 v94, v64
	v_mov_b32_e32 v95, v64
	v_mov_b32_e32 v104, v64
	v_mov_b32_e32 v105, v64
	v_mov_b32_e32 v106, v64
	v_mov_b32_e32 v107, v64
	v_mov_b32_e32 v108, v64
	v_mov_b32_e32 v109, v64
	v_mov_b32_e32 v110, v64
	v_mov_b32_e32 v111, v64
	v_mov_b32_e32 v120, v64
	v_mov_b32_e32 v121, v64
	v_mov_b32_e32 v122, v64
	v_mov_b32_e32 v123, v64
	v_mov_b32_e32 v124, v64
	v_mov_b32_e32 v125, v64
	v_mov_b32_e32 v126, v64
	v_mov_b32_e32 v127, v64
	s_branch .LBB0_81
	s_nop 0
	s_nop 0
	s_nop 0
	s_nop 0

.LBB0_185:
	s_ashr_i32 s1, s0, 31
	s_lshl_b64 s[4:5], s[0:1], 18
	v_readlane_b32 s1, v255, 26
	s_add_u32 s1, s1, s4
	v_readlane_b32 s4, v255, 34
	s_addc_u32 s4, s4, s5
	s_ashr_i32 s17, s16, 31
	s_lshl_b64 s[20:21], s[16:17], 7
	s_add_u32 s18, s1, s20
	s_addc_u32 s19, s4, s21
	s_and_b64 s[4:5], s[40:41], exec
	s_cselect_b32 s1, s19, s11
	s_cselect_b32 s17, s18, s10
	s_cmp_eq_u32 s12, 0
	s_cselect_b64 s[6:7], -1, 0
	s_and_b64 s[12:13], s[6:7], exec
	s_cselect_b32 s4, 0x40000, 0
	s_cmp_eq_u32 s35, 0
	s_mov_b32 s97, s35
	s_cselect_b32 s12, 0x40000, 0
	s_ashr_i32 s35, s34, 31
	s_lshl_b64 s[30:31], s[34:35], 19
	v_readlane_b32 s13, v255, 28
	s_add_u32 s13, s13, s30
	v_readlane_b32 s30, v255, 30
	s_addc_u32 s31, s30, s31
	s_add_u32 s30, s13, s20
	s_addc_u32 s31, s31, s21
	s_and_b64 s[20:21], s[40:41], exec
	s_cselect_b32 s13, s31, s9
	s_cselect_b32 s20, s30, s8
	s_add_i32 s21, s3, -2
	s_add_u32 s35, s8, 0x100
	s_addc_u32 s96, s9, 0
	s_mov_b32 s5, 0
	s_add_u32 s8, s10, 0x80
	s_addc_u32 s9, s11, 0
	v_lshl_add_u64 v[210:211], v[206:207], 0, s[4:5]
	v_lshl_add_u64 v[212:213], v[208:209], 0, s[4:5]
	s_branch .LBB0_187
	s_nop 0
	s_nop 0
	s_nop 0
	s_nop 0

.LBB0_584:
	s_cmp_eq_u32 s12, 0
	s_cselect_b64 s[6:7], -1, 0
	s_and_b64 s[10:11], s[6:7], exec
	s_cselect_b32 s64, 0xb0000, 0
	s_cmp_eq_u32 s52, 0
	s_cselect_b32 s12, 0xb0000, 0
	s_add_u32 s13, s8, 0x100
	s_addc_u32 s37, s9, 0
	s_add_u32 s8, s4, 0x80
	s_addc_u32 s9, s5, 0
	v_lshl_add_u64 v[0:1], s[8:9], 0, v[198:199]
	v_lshl_add_u64 v[206:207], v[0:1], 0, s[64:65]
	v_lshl_add_u64 v[0:1], s[8:9], 0, v[200:201]
	v_mov_b32_e32 v160, v161
	v_lshl_add_u64 v[208:209], v[0:1], 0, s[64:65]
	s_waitcnt lgkmcnt(0)
	v_mov_b32_e32 v162, v161
	v_mov_b32_e32 v163, v161
	v_mov_b32_e32 v64, 0
	v_mov_b64_e32 v[0:1], v[160:161]
	v_mov_b64_e32 v[4:5], v[160:161]
	v_mov_b64_e32 v[16:17], v[160:161]
	v_mov_b64_e32 v[20:21], v[160:161]
	v_mov_b64_e32 v[32:33], v[160:161]
	v_mov_b64_e32 v[36:37], v[160:161]
	v_mov_b64_e32 v[48:49], v[160:161]
	v_mov_b64_e32 v[52:53], v[160:161]
	v_mov_b64_e32 v[8:9], v[160:161]
	v_mov_b64_e32 v[12:13], v[160:161]
	v_mov_b64_e32 v[24:25], v[160:161]
	v_mov_b64_e32 v[28:29], v[160:161]
	v_mov_b64_e32 v[40:41], v[160:161]
	v_mov_b64_e32 v[44:45], v[160:161]
	v_mov_b64_e32 v[56:57], v[160:161]
	v_mov_b64_e32 v[60:61], v[160:161]
	s_mov_b32 s54, -2
	s_mov_b64 s[8:9], 0
	v_mov_b64_e32 v[2:3], v[162:163]
	v_mov_b64_e32 v[6:7], v[162:163]
	v_mov_b64_e32 v[18:19], v[162:163]
	v_mov_b64_e32 v[22:23], v[162:163]
	v_mov_b64_e32 v[34:35], v[162:163]
	v_mov_b64_e32 v[38:39], v[162:163]
	v_mov_b64_e32 v[50:51], v[162:163]
	v_mov_b64_e32 v[54:55], v[162:163]
	v_mov_b64_e32 v[10:11], v[162:163]
	v_mov_b64_e32 v[14:15], v[162:163]
	v_mov_b64_e32 v[26:27], v[162:163]
	v_mov_b64_e32 v[30:31], v[162:163]
	v_mov_b64_e32 v[42:43], v[162:163]
	v_mov_b64_e32 v[46:47], v[162:163]
	v_mov_b64_e32 v[58:59], v[162:163]
	v_mov_b64_e32 v[62:63], v[162:163]
	v_mov_b32_e32 v65, v64
	v_mov_b32_e32 v66, v64
	v_mov_b32_e32 v67, v64
	v_mov_b32_e32 v68, v64
	v_mov_b32_e32 v69, v64
	v_mov_b32_e32 v70, v64
	v_mov_b32_e32 v71, v64
	v_mov_b32_e32 v80, v64
	v_mov_b32_e32 v81, v64
	v_mov_b32_e32 v82, v64
	v_mov_b32_e32 v83, v64
	v_mov_b32_e32 v84, v64
	v_mov_b32_e32 v85, v64
	v_mov_b32_e32 v86, v64
	v_mov_b32_e32 v87, v64
	v_mov_b32_e32 v112, v64
	v_mov_b32_e32 v113, v64
	v_mov_b32_e32 v114, v64
	v_mov_b32_e32 v115, v64
	v_mov_b32_e32 v116, v64
	v_mov_b32_e32 v117, v64
	v_mov_b32_e32 v118, v64
	v_mov_b32_e32 v119, v64
	s_waitcnt vmcnt(0)
	v_mov_b32_e32 v128, v64
	v_mov_b32_e32 v129, v64
	v_mov_b32_e32 v130, v64
	v_mov_b32_e32 v131, v64
	v_mov_b32_e32 v132, v64
	v_mov_b32_e32 v133, v64
	v_mov_b32_e32 v134, v64
	v_mov_b32_e32 v135, v64
	v_mov_b32_e32 v72, v64
	v_mov_b32_e32 v73, v64
	v_mov_b32_e32 v74, v64
	v_mov_b32_e32 v75, v64
	v_mov_b32_e32 v76, v64
	v_mov_b32_e32 v77, v64
	v_mov_b32_e32 v78, v64
	v_mov_b32_e32 v79, v64
	v_mov_b32_e32 v88, v64
	v_mov_b32_e32 v89, v64
	v_mov_b32_e32 v90, v64
	v_mov_b32_e32 v91, v64
	v_mov_b32_e32 v92, v64
	v_mov_b32_e32 v93, v64
	v_mov_b32_e32 v94, v64
	v_mov_b32_e32 v95, v64
	v_mov_b32_e32 v120, v64
	v_mov_b32_e32 v121, v64
	v_mov_b32_e32 v122, v64
	v_mov_b32_e32 v123, v64
	v_mov_b32_e32 v124, v64
	v_mov_b32_e32 v125, v64
	v_mov_b32_e32 v126, v64
	v_mov_b32_e32 v127, v64
	v_mov_b32_e32 v136, v64
	v_mov_b32_e32 v137, v64
	v_mov_b32_e32 v138, v64
	v_mov_b32_e32 v139, v64
	v_mov_b32_e32 v140, v64
	v_mov_b32_e32 v141, v64
	v_mov_b32_e32 v142, v64
	v_mov_b32_e32 v143, v64
	s_branch .LBB0_586
	s_nop 0
	s_nop 0
	s_nop 0

.LBB0_624:
	s_cmp_eq_u32 s3, 0
	s_cselect_b64 s[0:1], -1, 0
	s_and_b64 s[8:9], s[0:1], exec
	s_cselect_b32 s64, 0xb0000, 0
	s_cmp_eq_u32 s20, 0
	s_cselect_b32 s3, 0xb0000, 0
	s_add_u32 s12, s6, 0x100
	s_addc_u32 s13, s7, 0
	s_add_u32 s6, s48, 0x80
	s_addc_u32 s7, s49, 0
	v_lshl_add_u64 v[0:1], s[6:7], 0, v[220:221]
	v_lshl_add_u64 v[224:225], v[0:1], 0, s[64:65]
	v_lshl_add_u64 v[0:1], s[6:7], 0, v[222:223]
	v_mov_b32_e32 v160, v161
	v_lshl_add_u64 v[226:227], v[0:1], 0, s[64:65]
	s_waitcnt lgkmcnt(0)
	v_mov_b32_e32 v162, v161
	v_mov_b32_e32 v163, v161
	v_mov_b32_e32 v64, 0
	v_mov_b64_e32 v[0:1], v[160:161]
	v_mov_b64_e32 v[4:5], v[160:161]
	v_mov_b64_e32 v[16:17], v[160:161]
	v_mov_b64_e32 v[20:21], v[160:161]
	v_mov_b64_e32 v[32:33], v[160:161]
	v_mov_b64_e32 v[36:37], v[160:161]
	v_mov_b64_e32 v[48:49], v[160:161]
	v_mov_b64_e32 v[52:53], v[160:161]
	v_mov_b64_e32 v[8:9], v[160:161]
	v_mov_b64_e32 v[12:13], v[160:161]
	v_mov_b64_e32 v[24:25], v[160:161]
	v_mov_b64_e32 v[28:29], v[160:161]
	v_mov_b64_e32 v[40:41], v[160:161]
	v_mov_b64_e32 v[44:45], v[160:161]
	v_mov_b64_e32 v[56:57], v[160:161]
	v_mov_b64_e32 v[60:61], v[160:161]
	s_mov_b32 s17, -2
	s_mov_b64 s[6:7], 0
	v_mov_b64_e32 v[2:3], v[162:163]
	v_mov_b64_e32 v[6:7], v[162:163]
	v_mov_b64_e32 v[18:19], v[162:163]
	v_mov_b64_e32 v[22:23], v[162:163]
	v_mov_b64_e32 v[34:35], v[162:163]
	v_mov_b64_e32 v[38:39], v[162:163]
	v_mov_b64_e32 v[50:51], v[162:163]
	v_mov_b64_e32 v[54:55], v[162:163]
	v_mov_b64_e32 v[10:11], v[162:163]
	v_mov_b64_e32 v[14:15], v[162:163]
	v_mov_b64_e32 v[26:27], v[162:163]
	v_mov_b64_e32 v[30:31], v[162:163]
	v_mov_b64_e32 v[42:43], v[162:163]
	v_mov_b64_e32 v[46:47], v[162:163]
	v_mov_b64_e32 v[58:59], v[162:163]
	v_mov_b64_e32 v[62:63], v[162:163]
	v_mov_b32_e32 v65, v64
	v_mov_b32_e32 v66, v64
	v_mov_b32_e32 v67, v64
	v_mov_b32_e32 v68, v64
	v_mov_b32_e32 v69, v64
	v_mov_b32_e32 v70, v64
	v_mov_b32_e32 v71, v64
	v_mov_b32_e32 v80, v64
	v_mov_b32_e32 v81, v64
	v_mov_b32_e32 v82, v64
	v_mov_b32_e32 v83, v64
	v_mov_b32_e32 v84, v64
	v_mov_b32_e32 v85, v64
	v_mov_b32_e32 v86, v64
	v_mov_b32_e32 v87, v64
	v_mov_b32_e32 v96, v64
	v_mov_b32_e32 v97, v64
	v_mov_b32_e32 v98, v64
	v_mov_b32_e32 v99, v64
	v_mov_b32_e32 v100, v64
	v_mov_b32_e32 v101, v64
	v_mov_b32_e32 v102, v64
	v_mov_b32_e32 v103, v64
	v_mov_b32_e32 v112, v64
	v_mov_b32_e32 v113, v64
	v_mov_b32_e32 v114, v64
	v_mov_b32_e32 v115, v64
	v_mov_b32_e32 v116, v64
	v_mov_b32_e32 v117, v64
	v_mov_b32_e32 v118, v64
	v_mov_b32_e32 v119, v64
	v_mov_b32_e32 v72, v64
	v_mov_b32_e32 v73, v64
	v_mov_b32_e32 v74, v64
	v_mov_b32_e32 v75, v64
	v_mov_b32_e32 v76, v64
	v_mov_b32_e32 v77, v64
	v_mov_b32_e32 v78, v64
	v_mov_b32_e32 v79, v64
	v_mov_b32_e32 v88, v64
	v_mov_b32_e32 v89, v64
	v_mov_b32_e32 v90, v64
	v_mov_b32_e32 v91, v64
	v_mov_b32_e32 v92, v64
	v_mov_b32_e32 v93, v64
	v_mov_b32_e32 v94, v64
	v_mov_b32_e32 v95, v64
	v_mov_b32_e32 v104, v64
	v_mov_b32_e32 v105, v64
	v_mov_b32_e32 v106, v64
	v_mov_b32_e32 v107, v64
	v_mov_b32_e32 v108, v64
	v_mov_b32_e32 v109, v64
	v_mov_b32_e32 v110, v64
	v_mov_b32_e32 v111, v64
	v_mov_b32_e32 v120, v64
	v_mov_b32_e32 v121, v64
	v_mov_b32_e32 v122, v64
	v_mov_b32_e32 v123, v64
	v_mov_b32_e32 v124, v64
	v_mov_b32_e32 v125, v64
	v_mov_b32_e32 v126, v64
	v_mov_b32_e32 v127, v64
	s_branch .LBB0_626
	s_nop 0
	s_nop 0
	s_nop 0
	s_nop 0

.LBB0_720:
	s_ashr_i32 s29, s28, 31
	s_lshl_b64 s[4:5], s[28:29], 18
	s_add_u32 s34, s14, s4
	s_addc_u32 s35, s15, s5
	s_and_b64 s[4:5], s[36:37], exec
	s_cselect_b32 s17, s35, s3
	s_cselect_b32 s29, s34, s2
	s_cmp_eq_u32 s8, 0
	s_cselect_b64 s[4:5], -1, 0
	s_and_b64 s[6:7], s[4:5], exec
	s_cselect_b32 s64, 0x40000, 0
	s_cmp_eq_u32 s52, 0
	s_cselect_b32 s12, 0x40000, 0
	s_ashr_i32 s31, s30, 31
	s_lshl_b64 s[6:7], s[30:31], 19
	v_readlane_b32 s8, v255, 9
	s_add_u32 s40, s8, s6
	v_readlane_b32 s6, v255, 10
	s_addc_u32 s41, s6, s7
	s_and_b64 s[6:7], s[36:37], exec
	s_cselect_b32 s13, s41, s1
	s_cselect_b32 s31, s40, s0
	s_add_u32 s96, s0, 0x100
	s_addc_u32 s97, s1, 0
	s_add_u32 s0, s2, 0x80
	s_addc_u32 s1, s3, 0
	v_lshl_add_u64 v[0:1], s[0:1], 0, v[206:207]
	v_lshl_add_u64 v[210:211], v[0:1], 0, s[64:65]
	v_lshl_add_u64 v[0:1], s[0:1], 0, v[208:209]
	v_mov_b32_e32 v160, v161
	v_lshl_add_u64 v[212:213], v[0:1], 0, s[64:65]
	s_waitcnt lgkmcnt(0)
	v_mov_b32_e32 v162, v161
	v_mov_b32_e32 v163, v161
	v_mov_b32_e32 v64, 0
	v_mov_b64_e32 v[0:1], v[160:161]
	v_mov_b64_e32 v[4:5], v[160:161]
	v_mov_b64_e32 v[16:17], v[160:161]
	v_mov_b64_e32 v[20:21], v[160:161]
	v_mov_b64_e32 v[32:33], v[160:161]
	v_mov_b64_e32 v[36:37], v[160:161]
	v_mov_b64_e32 v[48:49], v[160:161]
	v_mov_b64_e32 v[52:53], v[160:161]
	v_mov_b64_e32 v[8:9], v[160:161]
	v_mov_b64_e32 v[12:13], v[160:161]
	v_mov_b64_e32 v[24:25], v[160:161]
	v_mov_b64_e32 v[28:29], v[160:161]
	v_mov_b64_e32 v[40:41], v[160:161]
	v_mov_b64_e32 v[44:45], v[160:161]
	v_mov_b64_e32 v[56:57], v[160:161]
	v_mov_b64_e32 v[60:61], v[160:161]
	s_mov_b32 s54, -2
	s_mov_b64 s[6:7], 0
	v_mov_b64_e32 v[2:3], v[162:163]
	v_mov_b64_e32 v[6:7], v[162:163]
	v_mov_b64_e32 v[18:19], v[162:163]
	v_mov_b64_e32 v[22:23], v[162:163]
	v_mov_b64_e32 v[34:35], v[162:163]
	v_mov_b64_e32 v[38:39], v[162:163]
	v_mov_b64_e32 v[50:51], v[162:163]
	v_mov_b64_e32 v[54:55], v[162:163]
	v_mov_b64_e32 v[10:11], v[162:163]
	v_mov_b64_e32 v[14:15], v[162:163]
	v_mov_b64_e32 v[26:27], v[162:163]
	v_mov_b64_e32 v[30:31], v[162:163]
	v_mov_b64_e32 v[42:43], v[162:163]
	v_mov_b64_e32 v[46:47], v[162:163]
	v_mov_b64_e32 v[58:59], v[162:163]
	v_mov_b64_e32 v[62:63], v[162:163]
	v_mov_b32_e32 v65, v64
	v_mov_b32_e32 v66, v64
	v_mov_b32_e32 v67, v64
	v_mov_b32_e32 v68, v64
	v_mov_b32_e32 v69, v64
	v_mov_b32_e32 v70, v64
	v_mov_b32_e32 v71, v64
	v_mov_b32_e32 v80, v64
	v_mov_b32_e32 v81, v64
	v_mov_b32_e32 v82, v64
	v_mov_b32_e32 v83, v64
	v_mov_b32_e32 v84, v64
	v_mov_b32_e32 v85, v64
	v_mov_b32_e32 v86, v64
	v_mov_b32_e32 v87, v64
	v_mov_b32_e32 v96, v64
	v_mov_b32_e32 v97, v64
	v_mov_b32_e32 v98, v64
	v_mov_b32_e32 v99, v64
	v_mov_b32_e32 v100, v64
	v_mov_b32_e32 v101, v64
	v_mov_b32_e32 v102, v64
	v_mov_b32_e32 v103, v64
	v_mov_b32_e32 v112, v64
	v_mov_b32_e32 v113, v64
	v_mov_b32_e32 v114, v64
	v_mov_b32_e32 v115, v64
	v_mov_b32_e32 v116, v64
	v_mov_b32_e32 v117, v64
	v_mov_b32_e32 v118, v64
	v_mov_b32_e32 v119, v64
	v_mov_b32_e32 v72, v64
	v_mov_b32_e32 v73, v64
	v_mov_b32_e32 v74, v64
	v_mov_b32_e32 v75, v64
	v_mov_b32_e32 v76, v64
	v_mov_b32_e32 v77, v64
	v_mov_b32_e32 v78, v64
	v_mov_b32_e32 v79, v64
	v_mov_b32_e32 v88, v64
	v_mov_b32_e32 v89, v64
	v_mov_b32_e32 v90, v64
	v_mov_b32_e32 v91, v64
	v_mov_b32_e32 v92, v64
	v_mov_b32_e32 v93, v64
	v_mov_b32_e32 v94, v64
	v_mov_b32_e32 v95, v64
	v_mov_b32_e32 v104, v64
	v_mov_b32_e32 v105, v64
	v_mov_b32_e32 v106, v64
	v_mov_b32_e32 v107, v64
	v_mov_b32_e32 v108, v64
	v_mov_b32_e32 v109, v64
	v_mov_b32_e32 v110, v64
	v_mov_b32_e32 v111, v64
	v_mov_b32_e32 v120, v64
	v_mov_b32_e32 v121, v64
	v_mov_b32_e32 v122, v64
	v_mov_b32_e32 v123, v64
	v_mov_b32_e32 v124, v64
	v_mov_b32_e32 v125, v64
	v_mov_b32_e32 v126, v64
	v_mov_b32_e32 v127, v64
	s_branch .LBB0_722
	s_nop 0
	s_nop 0
	s_nop 0
	s_nop 0
